# wout_v89 + GDN S_prev snapshot record layout [w][half][lane]: the scan's snapshot stores and the head-output fragment loads cover whole 128B lines
# speedup vs baseline: 1.0238x; 1.0238x over previous
.LBB0_905:
	s_andn2_b64 vcc, exec, s[0:1]
	s_cbranch_vccnz .LBB0_931
	v_mov_b32_e32 v185, v181
	s_movk_i32 s0, 0x3c0
	v_ashrrev_i32_e32 v167, 6, v185
	v_lshlrev_b32_e32 v192, 10, v167
	v_lshlrev_b32_e32 v0, 6, v185
	v_and_or_b32 v0, v0, s0, v192
	v_lshrrev_b32_e32 v2, 1, v185
	v_ashrrev_i32_e32 v1, 31, v0
	v_and_b32_e32 v168, 24, v2
	v_lshl_add_u64 v[0:1], v[0:1], 1, s[20:21]
	s_waitcnt vmcnt(16)
	v_lshlrev_b32_e32 v160, 1, v168
	v_mov_b32_e32 v161, 0
	v_and_b32_e32 v166, 63, v185
	v_lshl_add_u64 v[0:1], v[0:1], 0, v[160:161]
	s_mov_b64 s[4:5], 0x11048000
	v_lshl_add_u64 v[176:177], v[0:1], 0, s[4:5]
	v_lshl_or_b32 v0, v166, 4, v192
	v_ashrrev_i32_e32 v1, 31, v0
	v_lshlrev_b64 v[162:163], 1, v[0:1]
	v_lshl_or_b32 v206, v166, 3, v192
	v_lshlrev_b32_e32 v206, 1, v206
	v_mov_b32_e32 v207, 0
	s_mov_b32 s1, 0
	v_lshl_add_u64 v[164:165], s[20:21], 0, v[162:163]
	s_mov_b64 s[4:5], 0x13148000
	s_lshl_b32 s0, s2, 19
	v_lshl_add_u64 v[178:179], v[164:165], 0, s[4:5]
	s_lshl_b64 s[4:5], s[0:1], 1
	v_lshl_add_u64 v[8:9], v[176:177], 0, s[4:5]
	v_lshl_add_u64 v[16:17], v[178:179], 0, s[4:5]
	s_or_b32 s4, s0, 0x1000
	s_mov_b32 s5, s1
	s_lshl_b64 s[4:5], s[4:5], 1
	v_lshl_add_u64 v[24:25], v[176:177], 0, s[4:5]
	v_lshl_add_u64 v[32:33], v[178:179], 0, s[4:5]
	s_or_b32 s4, s0, 0x2000
	s_mov_b32 s5, s1
	s_lshl_b64 s[4:5], s[4:5], 1
	v_lshl_add_u64 v[40:41], v[176:177], 0, s[4:5]
	v_lshl_add_u64 v[48:49], v[178:179], 0, s[4:5]
	s_or_b32 s4, s0, 0x3000
	s_mov_b32 s5, s1
	s_lshl_b64 s[4:5], s[4:5], 1
	v_lshl_add_u64 v[56:57], v[176:177], 0, s[4:5]
	v_lshl_add_u64 v[64:65], v[178:179], 0, s[4:5]
	s_or_b32 s4, s0, 0x4000
	s_mov_b32 s5, s1
	s_lshl_b64 s[4:5], s[4:5], 1
	v_lshl_add_u64 v[72:73], v[176:177], 0, s[4:5]
	v_lshl_add_u64 v[80:81], v[178:179], 0, s[4:5]
	s_or_b32 s4, s0, 0x5000
	s_mov_b32 s5, s1
	s_lshl_b64 s[4:5], s[4:5], 1
	v_lshl_add_u64 v[88:89], v[176:177], 0, s[4:5]
	v_lshl_add_u64 v[96:97], v[178:179], 0, s[4:5]
	s_or_b32 s4, s0, 0x6000
	s_mov_b32 s5, s1
	s_lshl_b64 s[4:5], s[4:5], 1
	v_lshl_add_u64 v[104:105], v[176:177], 0, s[4:5]
	v_lshl_add_u64 v[108:109], v[178:179], 0, s[4:5]
	s_or_b32 s4, s0, 0x7000
	s_mov_b32 s5, s1
	s_lshl_b64 s[4:5], s[4:5], 1
	v_lshl_add_u64 v[116:117], v[176:177], 0, s[4:5]
	v_lshl_add_u64 v[124:125], v[178:179], 0, s[4:5]
	s_or_b32 s4, s0, 0x8000
	s_mov_b32 s5, s1
	s_lshl_b64 s[4:5], s[4:5], 1
	v_lshl_add_u64 v[132:133], v[176:177], 0, s[4:5]
	v_lshl_add_u64 v[140:141], v[178:179], 0, s[4:5]
	s_or_b32 s4, s0, 0x9000
	s_mov_b32 s5, s1
	s_lshl_b64 s[4:5], s[4:5], 1
	v_lshl_add_u64 v[148:149], v[176:177], 0, s[4:5]
	v_lshl_add_u64 v[156:157], v[178:179], 0, s[4:5]
	s_barrier
	global_load_dwordx4 v[0:3], v[8:9], off
	global_load_dwordx4 v[4:7], v[8:9], off offset:64
	s_nop 0
	global_load_dwordx4 v[8:11], v[16:17], off offset:16
	global_load_dwordx4 v[12:15], v[16:17], off
	s_nop 0
	global_load_dwordx4 v[16:19], v[24:25], off
	global_load_dwordx4 v[20:23], v[24:25], off offset:64
	s_nop 0
	global_load_dwordx4 v[24:27], v[32:33], off offset:16
	global_load_dwordx4 v[28:31], v[32:33], off
	s_nop 0
	global_load_dwordx4 v[32:35], v[40:41], off
	global_load_dwordx4 v[36:39], v[40:41], off offset:64
	s_nop 0
	global_load_dwordx4 v[40:43], v[48:49], off offset:16
	global_load_dwordx4 v[44:47], v[48:49], off
	s_nop 0
	global_load_dwordx4 v[48:51], v[56:57], off
	global_load_dwordx4 v[52:55], v[56:57], off offset:64
	s_nop 0
	global_load_dwordx4 v[56:59], v[64:65], off offset:16
	global_load_dwordx4 v[60:63], v[64:65], off
	s_nop 0
	global_load_dwordx4 v[64:67], v[72:73], off
	global_load_dwordx4 v[68:71], v[72:73], off offset:64
	s_nop 0
	global_load_dwordx4 v[72:75], v[80:81], off offset:16
	global_load_dwordx4 v[76:79], v[80:81], off
	s_nop 0
	global_load_dwordx4 v[80:83], v[88:89], off
	global_load_dwordx4 v[84:87], v[88:89], off offset:64
	s_nop 0
	global_load_dwordx4 v[88:91], v[96:97], off offset:16
	global_load_dwordx4 v[92:95], v[96:97], off
	s_nop 0
	global_load_dwordx4 v[96:99], v[104:105], off
	global_load_dwordx4 v[100:103], v[104:105], off offset:64
	s_nop 0
	global_load_dwordx4 v[104:107], v[108:109], off offset:16
	s_nop 0
	global_load_dwordx4 v[108:111], v[108:109], off
	s_nop 0
	global_load_dwordx4 v[112:115], v[116:117], off
	s_nop 0
	global_load_dwordx4 v[116:119], v[116:117], off offset:64
	s_nop 0
	global_load_dwordx4 v[120:123], v[124:125], off offset:16
	s_nop 0
	global_load_dwordx4 v[124:127], v[124:125], off
	s_nop 0
	global_load_dwordx4 v[128:131], v[132:133], off
	s_nop 0
	global_load_dwordx4 v[132:135], v[132:133], off offset:64
	s_nop 0
	global_load_dwordx4 v[136:139], v[140:141], off offset:16
	s_nop 0
	global_load_dwordx4 v[140:143], v[140:141], off
	s_nop 0
	global_load_dwordx4 v[144:147], v[148:149], off
	s_nop 0
	global_load_dwordx4 v[148:151], v[148:149], off offset:64
	s_nop 0
	global_load_dwordx4 v[152:155], v[156:157], off offset:16
	s_nop 0
	global_load_dwordx4 v[156:159], v[156:157], off
	s_lshl_b32 s6, s2, 7
	s_mov_b64 s[4:5], 0x17348000
	s_mov_b32 s7, s1
	v_lshl_add_u64 v[186:187], s[20:21], 0, v[206:207]
	v_lshl_add_u64 v[186:187], v[186:187], 0, s[4:5]
	s_or_b32 s4, s0, 0x13000
	s_lshl_b32 s10, s2, 20
	s_lshl_b64 s[6:7], s[6:7], 13
	v_and_b32_e32 v184, 15, v185
	v_or_b32_e32 v166, 48, v166
	s_add_u32 s6, s20, s6
	v_mul_u32_u24_e32 v169, 0x48, v184
	v_mul_u32_u24_e32 v166, 0x48, v166
	s_addc_u32 s7, s21, s7
	v_lshl_or_b32 v164, v167, 5, v168
	v_lshlrev_b32_e32 v165, 1, v169
	v_lshlrev_b32_e32 v166, 1, v166
	v_lshl_add_u64 v[188:189], s[6:7], 0, v[206:207]
	v_mov_b32_e32 v162, v161
	v_mov_b32_e32 v163, v161
	v_add_u32_e32 v193, v164, v165
	v_add_u32_e32 v194, v164, v166
	v_add_u32_e32 v195, v165, v160
	v_add_u32_e32 v196, v166, v160
	v_mov_b32_e32 v160, v161
	v_mov_b64_e32 v[174:175], v[162:163]
	v_mov_b64_e32 v[170:171], v[162:163]
	v_mov_b64_e32 v[166:167], v[162:163]
	s_mov_b64 s[6:7], 0
	s_mov_b32 s11, 0x17348000
	s_mov_b32 s12, 0x1734a000
	s_mov_b32 s13, 0x1734c000
	s_mov_b32 s14, 0x1734e000
	s_mov_b32 s15, 0x17350000
	s_mov_b32 s16, 0x17352000
	s_mov_b32 s17, 0x17354000
	s_mov_b32 s29, 0x17356000
	v_mov_b64_e32 v[172:173], v[160:161]
	v_mov_b64_e32 v[168:169], v[160:161]
	v_mov_b64_e32 v[164:165], v[160:161]
	s_mov_b32 s34, 0
	s_branch .LBB0_908

.LBB0_908:
	v_lshl_add_u64 v[190:191], v[188:189], 0, s[6:7]
	v_cvt_pk_bf16_f32 v164, v164, v165
	v_cvt_pk_bf16_f32 v165, v166, v167
	v_cvt_pk_bf16_f32 v167, v170, v171
	v_cvt_pk_bf16_f32 v170, v160, v161
	v_add_co_u32_e32 v160, vcc, s11, v190
	v_cvt_pk_bf16_f32 v166, v168, v169
	v_cvt_pk_bf16_f32 v168, v172, v173
	v_cvt_pk_bf16_f32 v169, v174, v175
	v_cvt_pk_bf16_f32 v171, v162, v163
	v_addc_co_u32_e32 v161, vcc, 0, v191, vcc
	ds_write_b64 v193, v[164:165]
	ds_write_b64 v193, v[166:167] offset:2304
	ds_write_b64 v193, v[168:169] offset:4608
	ds_write_b64 v194, v[170:171]
	global_store_dwordx4 v[160:161], v[164:167], off
	global_store_dwordx4 v[160:161], v[168:171], off offset:1024
	s_waitcnt lgkmcnt(0)
	s_barrier
	ds_read_b128 v[164:167], v195
	ds_read_b128 v[168:171], v195 offset:64
	s_waitcnt vmcnt(16)
	v_lshlrev_b32_e32 v160, 16, v12
	v_and_b32_e32 v161, 0xffff0000, v12
	v_lshlrev_b32_e32 v162, 16, v13
	v_and_b32_e32 v163, 0xffff0000, v13
	ds_read_b128 v[172:175], v195 offset:2368
	ds_read_b128 v[198:201], v195 offset:4672
	s_waitcnt lgkmcnt(3)
	v_mfma_f32_16x16x32_bf16 v[160:163], v[0:3], v[164:167], v[160:163]
	v_lshlrev_b32_e32 v164, 16, v14
	v_and_b32_e32 v165, 0xffff0000, v14
	v_lshlrev_b32_e32 v166, 16, v15
	s_waitcnt lgkmcnt(2)
	v_mfma_f32_16x16x32_bf16 v[160:163], v[4:7], v[168:171], v[160:163]
	ds_read_b128 v[168:171], v195 offset:2304
	v_and_b32_e32 v167, 0xffff0000, v15
	ds_read_b128 v[202:205], v196 offset:64
	s_cmpk_lt_u32 s34, 0x76
	s_waitcnt lgkmcnt(1)
	v_mfma_f32_16x16x32_bf16 v[164:167], v[0:3], v[168:171], v[164:167]
	v_lshlrev_b32_e32 v168, 16, v8
	v_and_b32_e32 v169, 0xffff0000, v8
	v_lshlrev_b32_e32 v170, 16, v9
	v_mfma_f32_16x16x32_bf16 v[164:167], v[4:7], v[172:175], v[164:167]
	ds_read_b128 v[172:175], v195 offset:4608
	v_and_b32_e32 v171, 0xffff0000, v9
	s_cselect_b64 s[8:9], -1, 0
	s_and_b64 vcc, exec, s[8:9]
	s_waitcnt lgkmcnt(0)
	v_mfma_f32_16x16x32_bf16 v[168:171], v[0:3], v[172:175], v[168:171]
	v_lshlrev_b32_e32 v172, 16, v10
	v_and_b32_e32 v173, 0xffff0000, v10
	v_lshlrev_b32_e32 v174, 16, v11
	v_mfma_f32_16x16x32_bf16 v[168:171], v[4:7], v[198:201], v[168:171]
	ds_read_b128 v[198:201], v196
	v_and_b32_e32 v175, 0xffff0000, v11
	s_waitcnt lgkmcnt(0)
	s_nop 0
	v_mfma_f32_16x16x32_bf16 v[172:175], v[0:3], v[198:201], v[172:175]
	v_mfma_f32_16x16x32_bf16 v[172:175], v[4:7], v[202:205], v[172:175]
	s_cbranch_vccz .LBB0_910
	s_add_i32 s0, s4, 0xffff7000
	s_lshl_b64 s[24:25], s[0:1], 1
	v_lshl_add_u64 v[4:5], v[176:177], 0, s[24:25]
	v_lshl_add_u64 v[12:13], v[178:179], 0, s[24:25]
	global_load_dwordx4 v[0:3], v[4:5], off
	s_nop 0
	global_load_dwordx4 v[4:7], v[4:5], off offset:64
	s_nop 0
	global_load_dwordx4 v[8:11], v[12:13], off offset:16
	s_nop 0
	global_load_dwordx4 v[12:15], v[12:13], off
.LBB0_910:
	v_cvt_pk_bf16_f32 v160, v160, v161
	v_cvt_pk_bf16_f32 v161, v162, v163
	v_cvt_pk_bf16_f32 v162, v164, v165
	v_cvt_pk_bf16_f32 v164, v168, v169
	v_add_co_u32_e32 v168, vcc, s12, v190
	v_cvt_pk_bf16_f32 v163, v166, v167
	v_cvt_pk_bf16_f32 v165, v170, v171
	v_cvt_pk_bf16_f32 v166, v172, v173
	v_cvt_pk_bf16_f32 v167, v174, v175
	v_addc_co_u32_e32 v169, vcc, 0, v191, vcc
	ds_write_b64 v193, v[160:161] offset:9216
	ds_write_b64 v193, v[162:163] offset:11520
	ds_write_b64 v193, v[164:165] offset:13824
	ds_write_b64 v194, v[166:167] offset:9216
	global_store_dwordx4 v[168:169], v[160:163], off
	global_store_dwordx4 v[168:169], v[164:167], off offset:1024
	s_waitcnt lgkmcnt(0)
	s_barrier
	ds_read_b128 v[164:167], v195 offset:9216
	ds_read_b128 v[168:171], v195 offset:9280
	s_waitcnt vmcnt(16)
	v_lshlrev_b32_e32 v160, 16, v28
	v_and_b32_e32 v161, 0xffff0000, v28
	v_lshlrev_b32_e32 v162, 16, v29
	v_and_b32_e32 v163, 0xffff0000, v29
	ds_read_b128 v[172:175], v195 offset:11584
	ds_read_b128 v[198:201], v195 offset:13888
	s_waitcnt lgkmcnt(3)
	v_mfma_f32_16x16x32_bf16 v[160:163], v[16:19], v[164:167], v[160:163]
	v_lshlrev_b32_e32 v164, 16, v30
	v_and_b32_e32 v165, 0xffff0000, v30
	v_lshlrev_b32_e32 v166, 16, v31
	s_waitcnt lgkmcnt(2)
	v_mfma_f32_16x16x32_bf16 v[160:163], v[20:23], v[168:171], v[160:163]
	ds_read_b128 v[168:171], v195 offset:11520
	v_and_b32_e32 v167, 0xffff0000, v31
	ds_read_b128 v[202:205], v196 offset:9280
	s_andn2_b64 vcc, exec, s[8:9]
	s_waitcnt lgkmcnt(1)
	v_mfma_f32_16x16x32_bf16 v[164:167], v[16:19], v[168:171], v[164:167]
	v_lshlrev_b32_e32 v168, 16, v24
	v_and_b32_e32 v169, 0xffff0000, v24
	v_lshlrev_b32_e32 v170, 16, v25
	v_mfma_f32_16x16x32_bf16 v[164:167], v[20:23], v[172:175], v[164:167]
	ds_read_b128 v[172:175], v195 offset:13824
	v_and_b32_e32 v171, 0xffff0000, v25
	s_waitcnt lgkmcnt(0)
	s_nop 0
	v_mfma_f32_16x16x32_bf16 v[168:171], v[16:19], v[172:175], v[168:171]
	v_lshlrev_b32_e32 v172, 16, v26
	v_and_b32_e32 v173, 0xffff0000, v26
	v_lshlrev_b32_e32 v174, 16, v27
	v_mfma_f32_16x16x32_bf16 v[168:171], v[20:23], v[198:201], v[168:171]
	ds_read_b128 v[198:201], v196 offset:9216
	v_and_b32_e32 v175, 0xffff0000, v27
	s_waitcnt lgkmcnt(0)
	s_nop 0
	v_mfma_f32_16x16x32_bf16 v[172:175], v[16:19], v[198:201], v[172:175]
	v_mfma_f32_16x16x32_bf16 v[172:175], v[20:23], v[202:205], v[172:175]
	s_cbranch_vccnz .LBB0_912
	s_add_i32 s0, s4, 0xffff8000
	s_lshl_b64 s[8:9], s[0:1], 1
	v_lshl_add_u64 v[20:21], v[176:177], 0, s[8:9]
	v_lshl_add_u64 v[28:29], v[178:179], 0, s[8:9]
	global_load_dwordx4 v[16:19], v[20:21], off
	s_nop 0
	global_load_dwordx4 v[20:23], v[20:21], off offset:64
	s_nop 0
	global_load_dwordx4 v[24:27], v[28:29], off offset:16
	s_nop 0
	global_load_dwordx4 v[28:31], v[28:29], off
.LBB0_912:
	v_cvt_pk_bf16_f32 v160, v160, v161
	v_cvt_pk_bf16_f32 v161, v162, v163
	v_cvt_pk_bf16_f32 v162, v164, v165
	v_cvt_pk_bf16_f32 v164, v168, v169
	v_add_co_u32_e32 v168, vcc, s13, v190
	v_cvt_pk_bf16_f32 v163, v166, v167
	v_cvt_pk_bf16_f32 v165, v170, v171
	v_cvt_pk_bf16_f32 v166, v172, v173
	v_cvt_pk_bf16_f32 v167, v174, v175
	v_addc_co_u32_e32 v169, vcc, 0, v191, vcc
	ds_write_b64 v193, v[160:161]
	ds_write_b64 v193, v[162:163] offset:2304
	ds_write_b64 v193, v[164:165] offset:4608
	ds_write_b64 v194, v[166:167]
	global_store_dwordx4 v[168:169], v[160:163], off
	global_store_dwordx4 v[168:169], v[164:167], off offset:1024
	s_waitcnt lgkmcnt(0)
	s_barrier
	ds_read_b128 v[164:167], v195
	ds_read_b128 v[168:171], v195 offset:64
	s_waitcnt vmcnt(16)
	v_lshlrev_b32_e32 v160, 16, v44
	v_and_b32_e32 v161, 0xffff0000, v44
	v_lshlrev_b32_e32 v162, 16, v45
	v_and_b32_e32 v163, 0xffff0000, v45
	ds_read_b128 v[172:175], v195 offset:2368
	ds_read_b128 v[198:201], v195 offset:4672
	s_waitcnt lgkmcnt(3)
	v_mfma_f32_16x16x32_bf16 v[160:163], v[32:35], v[164:167], v[160:163]
	v_lshlrev_b32_e32 v164, 16, v46
	v_and_b32_e32 v165, 0xffff0000, v46
	v_lshlrev_b32_e32 v166, 16, v47
	s_waitcnt lgkmcnt(2)
	v_mfma_f32_16x16x32_bf16 v[160:163], v[36:39], v[168:171], v[160:163]
	ds_read_b128 v[168:171], v195 offset:2304
	v_and_b32_e32 v167, 0xffff0000, v47
	ds_read_b128 v[202:205], v196 offset:64
	s_cmpk_gt_u32 s34, 0x73
	s_waitcnt lgkmcnt(1)
	v_mfma_f32_16x16x32_bf16 v[164:167], v[32:35], v[168:171], v[164:167]
	v_lshlrev_b32_e32 v168, 16, v40
	v_and_b32_e32 v169, 0xffff0000, v40
	v_lshlrev_b32_e32 v170, 16, v41
	v_mfma_f32_16x16x32_bf16 v[164:167], v[36:39], v[172:175], v[164:167]
	ds_read_b128 v[172:175], v195 offset:4608
	v_and_b32_e32 v171, 0xffff0000, v41
	s_waitcnt lgkmcnt(0)
	s_nop 0
	v_mfma_f32_16x16x32_bf16 v[168:171], v[32:35], v[172:175], v[168:171]
	v_lshlrev_b32_e32 v172, 16, v42
	v_and_b32_e32 v173, 0xffff0000, v42
	v_lshlrev_b32_e32 v174, 16, v43
	v_mfma_f32_16x16x32_bf16 v[168:171], v[36:39], v[198:201], v[168:171]
	ds_read_b128 v[198:201], v196
	v_and_b32_e32 v175, 0xffff0000, v43
	s_waitcnt lgkmcnt(0)
	s_nop 0
	v_mfma_f32_16x16x32_bf16 v[172:175], v[32:35], v[198:201], v[172:175]
	v_mfma_f32_16x16x32_bf16 v[172:175], v[36:39], v[202:205], v[172:175]
	s_cbranch_scc1 .LBB0_914
	s_add_i32 s0, s4, 0xffff9000
	s_lshl_b64 s[8:9], s[0:1], 1
	v_lshl_add_u64 v[36:37], v[176:177], 0, s[8:9]
	v_lshl_add_u64 v[44:45], v[178:179], 0, s[8:9]
	global_load_dwordx4 v[32:35], v[36:37], off
	s_nop 0
	global_load_dwordx4 v[36:39], v[36:37], off offset:64
	s_nop 0
	global_load_dwordx4 v[40:43], v[44:45], off offset:16
	s_nop 0
	global_load_dwordx4 v[44:47], v[44:45], off
.LBB0_914:
	v_cvt_pk_bf16_f32 v160, v160, v161
	v_cvt_pk_bf16_f32 v161, v162, v163
	v_cvt_pk_bf16_f32 v162, v164, v165
	v_cvt_pk_bf16_f32 v164, v168, v169
	v_add_co_u32_e32 v168, vcc, s14, v190
	v_cvt_pk_bf16_f32 v163, v166, v167
	v_cvt_pk_bf16_f32 v165, v170, v171
	v_cvt_pk_bf16_f32 v166, v172, v173
	v_cvt_pk_bf16_f32 v167, v174, v175
	v_addc_co_u32_e32 v169, vcc, 0, v191, vcc
	ds_write_b64 v193, v[160:161] offset:9216
	ds_write_b64 v193, v[162:163] offset:11520
	ds_write_b64 v193, v[164:165] offset:13824
	ds_write_b64 v194, v[166:167] offset:9216
	global_store_dwordx4 v[168:169], v[160:163], off
	global_store_dwordx4 v[168:169], v[164:167], off offset:1024
	s_waitcnt lgkmcnt(0)
	s_barrier
	ds_read_b128 v[164:167], v195 offset:9216
	ds_read_b128 v[168:171], v195 offset:9280
	s_waitcnt vmcnt(16)
	v_lshlrev_b32_e32 v160, 16, v60
	v_and_b32_e32 v161, 0xffff0000, v60
	v_lshlrev_b32_e32 v162, 16, v61
	v_and_b32_e32 v163, 0xffff0000, v61
	ds_read_b128 v[172:175], v195 offset:11584
	ds_read_b128 v[198:201], v195 offset:13888
	s_waitcnt lgkmcnt(3)
	v_mfma_f32_16x16x32_bf16 v[160:163], v[48:51], v[164:167], v[160:163]
	v_lshlrev_b32_e32 v164, 16, v62
	v_and_b32_e32 v165, 0xffff0000, v62
	v_lshlrev_b32_e32 v166, 16, v63
	s_waitcnt lgkmcnt(2)
	v_mfma_f32_16x16x32_bf16 v[160:163], v[52:55], v[168:171], v[160:163]
	ds_read_b128 v[168:171], v195 offset:11520
	v_and_b32_e32 v167, 0xffff0000, v63
	ds_read_b128 v[202:205], v196 offset:9280
	s_cmpk_gt_u32 s34, 0x72
	s_waitcnt lgkmcnt(1)
	v_mfma_f32_16x16x32_bf16 v[164:167], v[48:51], v[168:171], v[164:167]
	v_lshlrev_b32_e32 v168, 16, v56
	v_and_b32_e32 v169, 0xffff0000, v56
	v_lshlrev_b32_e32 v170, 16, v57
	v_mfma_f32_16x16x32_bf16 v[164:167], v[52:55], v[172:175], v[164:167]
	ds_read_b128 v[172:175], v195 offset:13824
	v_and_b32_e32 v171, 0xffff0000, v57
	s_waitcnt lgkmcnt(0)
	s_nop 0
	v_mfma_f32_16x16x32_bf16 v[168:171], v[48:51], v[172:175], v[168:171]
	v_lshlrev_b32_e32 v172, 16, v58
	v_and_b32_e32 v173, 0xffff0000, v58
	v_lshlrev_b32_e32 v174, 16, v59
	v_mfma_f32_16x16x32_bf16 v[168:171], v[52:55], v[198:201], v[168:171]
	ds_read_b128 v[198:201], v196 offset:9216
	v_and_b32_e32 v175, 0xffff0000, v59
	s_waitcnt lgkmcnt(0)
	s_nop 0
	v_mfma_f32_16x16x32_bf16 v[172:175], v[48:51], v[198:201], v[172:175]
	v_mfma_f32_16x16x32_bf16 v[172:175], v[52:55], v[202:205], v[172:175]
	s_cbranch_scc1 .LBB0_916
	s_add_i32 s0, s4, 0xffffa000
	s_lshl_b64 s[8:9], s[0:1], 1
	v_lshl_add_u64 v[52:53], v[176:177], 0, s[8:9]
	v_lshl_add_u64 v[60:61], v[178:179], 0, s[8:9]
	global_load_dwordx4 v[48:51], v[52:53], off
	s_nop 0
	global_load_dwordx4 v[52:55], v[52:53], off offset:64
	s_nop 0
	global_load_dwordx4 v[56:59], v[60:61], off offset:16
	s_nop 0
	global_load_dwordx4 v[60:63], v[60:61], off
.LBB0_916:
	v_cvt_pk_bf16_f32 v160, v160, v161
	v_cvt_pk_bf16_f32 v161, v162, v163
	v_cvt_pk_bf16_f32 v162, v164, v165
	v_cvt_pk_bf16_f32 v164, v168, v169
	v_add_co_u32_e32 v168, vcc, s15, v190
	v_cvt_pk_bf16_f32 v163, v166, v167
	v_cvt_pk_bf16_f32 v165, v170, v171
	v_cvt_pk_bf16_f32 v166, v172, v173
	v_cvt_pk_bf16_f32 v167, v174, v175
	v_addc_co_u32_e32 v169, vcc, 0, v191, vcc
	ds_write_b64 v193, v[160:161]
	ds_write_b64 v193, v[162:163] offset:2304
	ds_write_b64 v193, v[164:165] offset:4608
	ds_write_b64 v194, v[166:167]
	global_store_dwordx4 v[168:169], v[160:163], off
	global_store_dwordx4 v[168:169], v[164:167], off offset:1024
	s_waitcnt lgkmcnt(0)
	s_barrier
	ds_read_b128 v[164:167], v195
	ds_read_b128 v[168:171], v195 offset:64
	s_waitcnt vmcnt(16)
	v_lshlrev_b32_e32 v160, 16, v76
	v_and_b32_e32 v161, 0xffff0000, v76
	v_lshlrev_b32_e32 v162, 16, v77
	v_and_b32_e32 v163, 0xffff0000, v77
	ds_read_b128 v[172:175], v195 offset:2368
	ds_read_b128 v[198:201], v195 offset:4672
	s_waitcnt lgkmcnt(3)
	v_mfma_f32_16x16x32_bf16 v[160:163], v[64:67], v[164:167], v[160:163]
	v_lshlrev_b32_e32 v164, 16, v78
	v_and_b32_e32 v165, 0xffff0000, v78
	v_lshlrev_b32_e32 v166, 16, v79
	s_waitcnt lgkmcnt(2)
	v_mfma_f32_16x16x32_bf16 v[160:163], v[68:71], v[168:171], v[160:163]
	ds_read_b128 v[168:171], v195 offset:2304
	v_and_b32_e32 v167, 0xffff0000, v79
	ds_read_b128 v[202:205], v196 offset:64
	s_cmpk_gt_u32 s34, 0x71
	s_waitcnt lgkmcnt(1)
	v_mfma_f32_16x16x32_bf16 v[164:167], v[64:67], v[168:171], v[164:167]
	v_lshlrev_b32_e32 v168, 16, v72
	v_and_b32_e32 v169, 0xffff0000, v72
	v_lshlrev_b32_e32 v170, 16, v73
	v_mfma_f32_16x16x32_bf16 v[164:167], v[68:71], v[172:175], v[164:167]
	ds_read_b128 v[172:175], v195 offset:4608
	v_and_b32_e32 v171, 0xffff0000, v73
	s_waitcnt lgkmcnt(0)
	s_nop 0
	v_mfma_f32_16x16x32_bf16 v[168:171], v[64:67], v[172:175], v[168:171]
	v_lshlrev_b32_e32 v172, 16, v74
	v_and_b32_e32 v173, 0xffff0000, v74
	v_lshlrev_b32_e32 v174, 16, v75
	v_mfma_f32_16x16x32_bf16 v[168:171], v[68:71], v[198:201], v[168:171]
	ds_read_b128 v[198:201], v196
	v_and_b32_e32 v175, 0xffff0000, v75
	s_waitcnt lgkmcnt(0)
	s_nop 0
	v_mfma_f32_16x16x32_bf16 v[172:175], v[64:67], v[198:201], v[172:175]
	v_mfma_f32_16x16x32_bf16 v[172:175], v[68:71], v[202:205], v[172:175]
	s_cbranch_scc1 .LBB0_918
	s_add_i32 s0, s4, 0xffffb000
	s_lshl_b64 s[8:9], s[0:1], 1
	v_lshl_add_u64 v[68:69], v[176:177], 0, s[8:9]
	v_lshl_add_u64 v[76:77], v[178:179], 0, s[8:9]
	global_load_dwordx4 v[64:67], v[68:69], off
	s_nop 0
	global_load_dwordx4 v[68:71], v[68:69], off offset:64
	s_nop 0
	global_load_dwordx4 v[72:75], v[76:77], off offset:16
	s_nop 0
	global_load_dwordx4 v[76:79], v[76:77], off
.LBB0_918:
	v_cvt_pk_bf16_f32 v160, v160, v161
	v_cvt_pk_bf16_f32 v161, v162, v163
	v_cvt_pk_bf16_f32 v162, v164, v165
	v_cvt_pk_bf16_f32 v164, v168, v169
	v_add_co_u32_e32 v168, vcc, s16, v190
	v_cvt_pk_bf16_f32 v163, v166, v167
	v_cvt_pk_bf16_f32 v165, v170, v171
	v_cvt_pk_bf16_f32 v166, v172, v173
	v_cvt_pk_bf16_f32 v167, v174, v175
	v_addc_co_u32_e32 v169, vcc, 0, v191, vcc
	ds_write_b64 v193, v[160:161] offset:9216
	ds_write_b64 v193, v[162:163] offset:11520
	ds_write_b64 v193, v[164:165] offset:13824
	ds_write_b64 v194, v[166:167] offset:9216
	global_store_dwordx4 v[168:169], v[160:163], off
	global_store_dwordx4 v[168:169], v[164:167], off offset:1024
	s_waitcnt lgkmcnt(0)
	s_barrier
	ds_read_b128 v[164:167], v195 offset:9216
	ds_read_b128 v[168:171], v195 offset:9280
	s_waitcnt vmcnt(16)
	v_lshlrev_b32_e32 v160, 16, v92
	v_and_b32_e32 v161, 0xffff0000, v92
	v_lshlrev_b32_e32 v162, 16, v93
	v_and_b32_e32 v163, 0xffff0000, v93
	ds_read_b128 v[172:175], v195 offset:11584
	ds_read_b128 v[198:201], v195 offset:13888
	s_waitcnt lgkmcnt(3)
	v_mfma_f32_16x16x32_bf16 v[160:163], v[80:83], v[164:167], v[160:163]
	v_lshlrev_b32_e32 v164, 16, v94
	v_and_b32_e32 v165, 0xffff0000, v94
	v_lshlrev_b32_e32 v166, 16, v95
	s_waitcnt lgkmcnt(2)
	v_mfma_f32_16x16x32_bf16 v[160:163], v[84:87], v[168:171], v[160:163]
	ds_read_b128 v[168:171], v195 offset:11520
	v_and_b32_e32 v167, 0xffff0000, v95
	ds_read_b128 v[202:205], v196 offset:9280
	s_cmpk_gt_u32 s34, 0x70
	s_waitcnt lgkmcnt(1)
	v_mfma_f32_16x16x32_bf16 v[164:167], v[80:83], v[168:171], v[164:167]
	v_lshlrev_b32_e32 v168, 16, v88
	v_and_b32_e32 v169, 0xffff0000, v88
	v_lshlrev_b32_e32 v170, 16, v89
	v_mfma_f32_16x16x32_bf16 v[164:167], v[84:87], v[172:175], v[164:167]
	ds_read_b128 v[172:175], v195 offset:13824
	v_and_b32_e32 v171, 0xffff0000, v89
	s_waitcnt lgkmcnt(0)
	s_nop 0
	v_mfma_f32_16x16x32_bf16 v[168:171], v[80:83], v[172:175], v[168:171]
	v_lshlrev_b32_e32 v172, 16, v90
	v_and_b32_e32 v173, 0xffff0000, v90
	v_lshlrev_b32_e32 v174, 16, v91
	v_mfma_f32_16x16x32_bf16 v[168:171], v[84:87], v[198:201], v[168:171]
	ds_read_b128 v[198:201], v196 offset:9216
	v_and_b32_e32 v175, 0xffff0000, v91
	s_waitcnt lgkmcnt(0)
	s_nop 0
	v_mfma_f32_16x16x32_bf16 v[172:175], v[80:83], v[198:201], v[172:175]
	v_mfma_f32_16x16x32_bf16 v[172:175], v[84:87], v[202:205], v[172:175]
	s_cbranch_scc1 .LBB0_920
	s_add_i32 s0, s4, 0xffffc000
	s_lshl_b64 s[8:9], s[0:1], 1
	v_lshl_add_u64 v[84:85], v[176:177], 0, s[8:9]
	v_lshl_add_u64 v[92:93], v[178:179], 0, s[8:9]
	global_load_dwordx4 v[80:83], v[84:85], off
	s_nop 0
	global_load_dwordx4 v[84:87], v[84:85], off offset:64
	s_nop 0
	global_load_dwordx4 v[88:91], v[92:93], off offset:16
	s_nop 0
	global_load_dwordx4 v[92:95], v[92:93], off
.LBB0_920:
	v_cvt_pk_bf16_f32 v160, v160, v161
	v_cvt_pk_bf16_f32 v161, v162, v163
	v_cvt_pk_bf16_f32 v162, v164, v165
	v_cvt_pk_bf16_f32 v164, v168, v169
	v_add_co_u32_e32 v168, vcc, s17, v190
	v_cvt_pk_bf16_f32 v163, v166, v167
	v_cvt_pk_bf16_f32 v165, v170, v171
	v_cvt_pk_bf16_f32 v166, v172, v173
	v_cvt_pk_bf16_f32 v167, v174, v175
	v_addc_co_u32_e32 v169, vcc, 0, v191, vcc
	ds_write_b64 v193, v[160:161]
	ds_write_b64 v193, v[162:163] offset:2304
	ds_write_b64 v193, v[164:165] offset:4608
	ds_write_b64 v194, v[166:167]
	global_store_dwordx4 v[168:169], v[160:163], off
	global_store_dwordx4 v[168:169], v[164:167], off offset:1024
	s_waitcnt lgkmcnt(0)
	s_barrier
	ds_read_b128 v[164:167], v195
	ds_read_b128 v[168:171], v195 offset:64
	s_waitcnt vmcnt(16)
	v_lshlrev_b32_e32 v160, 16, v108
	v_and_b32_e32 v161, 0xffff0000, v108
	v_lshlrev_b32_e32 v162, 16, v109
	v_and_b32_e32 v163, 0xffff0000, v109
	ds_read_b128 v[172:175], v195 offset:2368
	ds_read_b128 v[198:201], v195 offset:4672
	s_waitcnt lgkmcnt(3)
	v_mfma_f32_16x16x32_bf16 v[160:163], v[96:99], v[164:167], v[160:163]
	v_lshlrev_b32_e32 v164, 16, v110
	v_and_b32_e32 v165, 0xffff0000, v110
	v_lshlrev_b32_e32 v166, 16, v111
	s_waitcnt lgkmcnt(2)
	v_mfma_f32_16x16x32_bf16 v[160:163], v[100:103], v[168:171], v[160:163]
	ds_read_b128 v[168:171], v195 offset:2304
	v_and_b32_e32 v167, 0xffff0000, v111
	ds_read_b128 v[202:205], v196 offset:64
	s_cmpk_gt_u32 s34, 0x6f
	s_waitcnt lgkmcnt(1)
	v_mfma_f32_16x16x32_bf16 v[164:167], v[96:99], v[168:171], v[164:167]
	v_lshlrev_b32_e32 v168, 16, v104
	v_and_b32_e32 v169, 0xffff0000, v104
	v_lshlrev_b32_e32 v170, 16, v105
	v_mfma_f32_16x16x32_bf16 v[164:167], v[100:103], v[172:175], v[164:167]
	ds_read_b128 v[172:175], v195 offset:4608
	v_and_b32_e32 v171, 0xffff0000, v105
	s_waitcnt lgkmcnt(0)
	s_nop 0
	v_mfma_f32_16x16x32_bf16 v[168:171], v[96:99], v[172:175], v[168:171]
	v_lshlrev_b32_e32 v172, 16, v106
	v_and_b32_e32 v173, 0xffff0000, v106
	v_lshlrev_b32_e32 v174, 16, v107
	v_mfma_f32_16x16x32_bf16 v[168:171], v[100:103], v[198:201], v[168:171]
	ds_read_b128 v[198:201], v196
	v_and_b32_e32 v175, 0xffff0000, v107
	s_waitcnt lgkmcnt(0)
	s_nop 0
	v_mfma_f32_16x16x32_bf16 v[172:175], v[96:99], v[198:201], v[172:175]
	v_mfma_f32_16x16x32_bf16 v[172:175], v[100:103], v[202:205], v[172:175]
	s_cbranch_scc1 .LBB0_922
	s_add_i32 s0, s4, 0xffffd000
	s_lshl_b64 s[8:9], s[0:1], 1
	v_lshl_add_u64 v[100:101], v[176:177], 0, s[8:9]
	v_lshl_add_u64 v[108:109], v[178:179], 0, s[8:9]
	global_load_dwordx4 v[96:99], v[100:101], off
	s_nop 0
	global_load_dwordx4 v[100:103], v[100:101], off offset:64
	s_nop 0
	global_load_dwordx4 v[104:107], v[108:109], off offset:16
	s_nop 0
	global_load_dwordx4 v[108:111], v[108:109], off
.LBB0_922:
	v_cvt_pk_bf16_f32 v160, v160, v161
	v_cvt_pk_bf16_f32 v161, v162, v163
	v_cvt_pk_bf16_f32 v162, v164, v165
	v_cvt_pk_bf16_f32 v164, v168, v169
	v_add_co_u32_e32 v168, vcc, s29, v190
	v_cvt_pk_bf16_f32 v163, v166, v167
	v_cvt_pk_bf16_f32 v165, v170, v171
	v_cvt_pk_bf16_f32 v166, v172, v173
	v_cvt_pk_bf16_f32 v167, v174, v175
	v_addc_co_u32_e32 v169, vcc, 0, v191, vcc
	ds_write_b64 v193, v[160:161] offset:9216
	ds_write_b64 v193, v[162:163] offset:11520
	ds_write_b64 v193, v[164:165] offset:13824
	ds_write_b64 v194, v[166:167] offset:9216
	global_store_dwordx4 v[168:169], v[160:163], off
	global_store_dwordx4 v[168:169], v[164:167], off offset:1024
	s_waitcnt lgkmcnt(0)
	s_barrier
	ds_read_b128 v[164:167], v195 offset:9216
	ds_read_b128 v[168:171], v195 offset:9280
	s_waitcnt vmcnt(16)
	v_lshlrev_b32_e32 v160, 16, v124
	v_and_b32_e32 v161, 0xffff0000, v124
	v_lshlrev_b32_e32 v162, 16, v125
	v_and_b32_e32 v163, 0xffff0000, v125
	ds_read_b128 v[172:175], v195 offset:11584
	ds_read_b128 v[198:201], v195 offset:13888
	s_waitcnt lgkmcnt(3)
	v_mfma_f32_16x16x32_bf16 v[160:163], v[112:115], v[164:167], v[160:163]
	ds_read_b128 v[202:205], v196 offset:9280
	s_cmpk_gt_u32 s34, 0x6e
	s_waitcnt lgkmcnt(3)
	v_mfma_f32_16x16x32_bf16 v[164:167], v[116:119], v[168:171], v[160:163]
	ds_read_b128 v[168:171], v195 offset:11520
	s_nop 2
	v_lshlrev_b32_e32 v160, 16, v126
	v_and_b32_e32 v161, 0xffff0000, v126
	v_lshlrev_b32_e32 v162, 16, v127
	v_and_b32_e32 v163, 0xffff0000, v127
	s_waitcnt lgkmcnt(0)
	s_nop 0
	v_mfma_f32_16x16x32_bf16 v[160:163], v[112:115], v[168:171], v[160:163]
	v_mfma_f32_16x16x32_bf16 v[168:171], v[116:119], v[172:175], v[160:163]
	ds_read_b128 v[172:175], v195 offset:13824
	s_nop 5
	v_lshlrev_b32_e32 v160, 16, v120
	v_and_b32_e32 v161, 0xffff0000, v120
	v_lshlrev_b32_e32 v162, 16, v121
	v_and_b32_e32 v163, 0xffff0000, v121
	s_waitcnt lgkmcnt(0)
	s_nop 0
	v_mfma_f32_16x16x32_bf16 v[160:163], v[112:115], v[172:175], v[160:163]
	v_mfma_f32_16x16x32_bf16 v[172:175], v[116:119], v[198:201], v[160:163]
	ds_read_b128 v[198:201], v196 offset:9216
	s_nop 5
	v_lshlrev_b32_e32 v160, 16, v122
	v_and_b32_e32 v161, 0xffff0000, v122
	v_lshlrev_b32_e32 v162, 16, v123
	v_and_b32_e32 v163, 0xffff0000, v123
	s_waitcnt lgkmcnt(0)
	s_nop 0
	v_mfma_f32_16x16x32_bf16 v[160:163], v[112:115], v[198:201], v[160:163]
	v_mfma_f32_16x16x32_bf16 v[160:163], v[116:119], v[202:205], v[160:163]
	s_cbranch_scc1 .LBB0_924
	s_add_i32 s0, s4, 0xffffe000
	s_lshl_b64 s[8:9], s[0:1], 1
	v_lshl_add_u64 v[116:117], v[176:177], 0, s[8:9]
	v_lshl_add_u64 v[124:125], v[178:179], 0, s[8:9]
	global_load_dwordx4 v[112:115], v[116:117], off
	s_nop 0
	global_load_dwordx4 v[116:119], v[116:117], off offset:64
	s_nop 0
	global_load_dwordx4 v[120:123], v[124:125], off offset:16
	s_nop 0
	global_load_dwordx4 v[124:127], v[124:125], off
.LBB0_924:
	s_cmpk_gt_u32 s34, 0x77
	s_cselect_b64 s[8:9], -1, 0
	s_and_b64 vcc, exec, s[8:9]
	s_cbranch_vccnz .LBB0_927
	s_add_i32 s0, s10, s6
	s_add_i32 s0, s0, 0x10000
	v_cvt_pk_bf16_f32 v164, v164, v165
	v_cvt_pk_bf16_f32 v165, v166, v167
	v_cvt_pk_bf16_f32 v166, v168, v169
	v_cvt_pk_bf16_f32 v167, v170, v171
	v_cvt_pk_bf16_f32 v168, v172, v173
	v_cvt_pk_bf16_f32 v169, v174, v175
	v_cvt_pk_bf16_f32 v170, v160, v161
	v_cvt_pk_bf16_f32 v171, v162, v163
	v_lshl_add_u64 v[160:161], v[186:187], 0, s[0:1]
	ds_write_b64 v193, v[164:165]
	ds_write_b64 v193, v[166:167] offset:2304
	ds_write_b64 v193, v[168:169] offset:4608
	ds_write_b64 v194, v[170:171]
	global_store_dwordx4 v[160:161], v[164:167], off
	global_store_dwordx4 v[160:161], v[168:171], off offset:1024
	s_waitcnt lgkmcnt(0)
	s_barrier
	ds_read_b128 v[164:167], v195
	ds_read_b128 v[168:171], v195 offset:64
	s_waitcnt vmcnt(22)
	v_lshlrev_b32_e32 v160, 16, v140
	v_and_b32_e32 v161, 0xffff0000, v140
	v_lshlrev_b32_e32 v162, 16, v141
	v_and_b32_e32 v163, 0xffff0000, v141
	ds_read_b128 v[172:175], v195 offset:2368
	ds_read_b128 v[198:201], v195 offset:4672
	s_waitcnt lgkmcnt(3)
	v_mfma_f32_16x16x32_bf16 v[160:163], v[128:131], v[164:167], v[160:163]
	s_cmpk_gt_u32 s34, 0x6d
	ds_read_b128 v[202:205], v196 offset:64
	s_waitcnt lgkmcnt(3)
	v_mfma_f32_16x16x32_bf16 v[164:167], v[132:135], v[168:171], v[160:163]
	ds_read_b128 v[168:171], v195 offset:2304
	s_nop 2
	v_lshlrev_b32_e32 v160, 16, v142
	v_and_b32_e32 v161, 0xffff0000, v142
	v_lshlrev_b32_e32 v162, 16, v143
	v_and_b32_e32 v163, 0xffff0000, v143
	s_waitcnt lgkmcnt(0)
	s_nop 0
	v_mfma_f32_16x16x32_bf16 v[160:163], v[128:131], v[168:171], v[160:163]
	v_mfma_f32_16x16x32_bf16 v[168:171], v[132:135], v[172:175], v[160:163]
	ds_read_b128 v[172:175], v195 offset:4608
	s_nop 5
	v_lshlrev_b32_e32 v160, 16, v136
	v_and_b32_e32 v161, 0xffff0000, v136
	v_lshlrev_b32_e32 v162, 16, v137
	v_and_b32_e32 v163, 0xffff0000, v137
	s_waitcnt lgkmcnt(0)
	s_nop 0
	v_mfma_f32_16x16x32_bf16 v[160:163], v[128:131], v[172:175], v[160:163]
	v_mfma_f32_16x16x32_bf16 v[172:175], v[132:135], v[198:201], v[160:163]
	ds_read_b128 v[198:201], v196
	s_nop 5
	v_lshlrev_b32_e32 v160, 16, v138
	v_and_b32_e32 v161, 0xffff0000, v138
	v_lshlrev_b32_e32 v162, 16, v139
	v_and_b32_e32 v163, 0xffff0000, v139
	s_waitcnt lgkmcnt(0)
	s_nop 0
	v_mfma_f32_16x16x32_bf16 v[160:163], v[128:131], v[198:201], v[160:163]
	v_mfma_f32_16x16x32_bf16 v[160:163], v[132:135], v[202:205], v[160:163]
	s_cbranch_scc1 .LBB0_927
	s_add_i32 s0, s4, 0xfffff000
	s_lshl_b64 s[24:25], s[0:1], 1
	v_lshl_add_u64 v[132:133], v[176:177], 0, s[24:25]
	v_lshl_add_u64 v[140:141], v[178:179], 0, s[24:25]
	global_load_dwordx4 v[128:131], v[132:133], off
	s_nop 0
	global_load_dwordx4 v[132:135], v[132:133], off offset:64
	s_nop 0
	global_load_dwordx4 v[136:139], v[140:141], off offset:16
	s_nop 0
	global_load_dwordx4 v[140:143], v[140:141], off
.LBB0_927:
	s_cmpk_gt_u32 s34, 0x76
	s_cbranch_scc1 .LBB0_907
	s_add_i32 s0, s10, s6
	s_add_i32 s0, s0, 0x12000
	v_cvt_pk_bf16_f32 v164, v164, v165
	v_cvt_pk_bf16_f32 v165, v166, v167
	v_cvt_pk_bf16_f32 v166, v168, v169
	v_cvt_pk_bf16_f32 v167, v170, v171
	v_cvt_pk_bf16_f32 v168, v172, v173
	v_cvt_pk_bf16_f32 v169, v174, v175
	v_cvt_pk_bf16_f32 v170, v160, v161
	v_cvt_pk_bf16_f32 v171, v162, v163
	v_lshl_add_u64 v[160:161], v[186:187], 0, s[0:1]
	ds_write_b64 v193, v[164:165] offset:9216
	ds_write_b64 v193, v[166:167] offset:11520
	ds_write_b64 v193, v[168:169] offset:13824
	ds_write_b64 v194, v[170:171] offset:9216
	global_store_dwordx4 v[160:161], v[164:167], off
	global_store_dwordx4 v[160:161], v[168:171], off offset:1024
	s_waitcnt lgkmcnt(0)
	s_barrier
	ds_read_b128 v[164:167], v195 offset:9216
	ds_read_b128 v[168:171], v195 offset:9280
	s_waitcnt vmcnt(18)
	v_lshlrev_b32_e32 v160, 16, v156
	v_and_b32_e32 v161, 0xffff0000, v156
	v_lshlrev_b32_e32 v162, 16, v157
	v_and_b32_e32 v163, 0xffff0000, v157
	ds_read_b128 v[172:175], v195 offset:11584
	ds_read_b128 v[198:201], v195 offset:13888
	s_waitcnt lgkmcnt(3)
	v_mfma_f32_16x16x32_bf16 v[160:163], v[144:147], v[164:167], v[160:163]
	s_cmpk_gt_u32 s34, 0x6c
	ds_read_b128 v[202:205], v196 offset:9280
	s_waitcnt lgkmcnt(3)
	v_mfma_f32_16x16x32_bf16 v[164:167], v[148:151], v[168:171], v[160:163]
	ds_read_b128 v[168:171], v195 offset:11520
	s_nop 2
	v_lshlrev_b32_e32 v160, 16, v158
	v_and_b32_e32 v161, 0xffff0000, v158
	v_lshlrev_b32_e32 v162, 16, v159
	v_and_b32_e32 v163, 0xffff0000, v159
	s_waitcnt lgkmcnt(0)
	s_nop 0
	v_mfma_f32_16x16x32_bf16 v[160:163], v[144:147], v[168:171], v[160:163]
	v_mfma_f32_16x16x32_bf16 v[168:171], v[148:151], v[172:175], v[160:163]
	ds_read_b128 v[172:175], v195 offset:13824
	s_nop 5
	v_lshlrev_b32_e32 v160, 16, v152
	v_and_b32_e32 v161, 0xffff0000, v152
	v_lshlrev_b32_e32 v162, 16, v153
	v_and_b32_e32 v163, 0xffff0000, v153
	s_waitcnt lgkmcnt(0)
	s_nop 0
	v_mfma_f32_16x16x32_bf16 v[160:163], v[144:147], v[172:175], v[160:163]
	v_mfma_f32_16x16x32_bf16 v[172:175], v[148:151], v[198:201], v[160:163]
	ds_read_b128 v[198:201], v196 offset:9216
	s_nop 5
	v_lshlrev_b32_e32 v160, 16, v154
	v_and_b32_e32 v161, 0xffff0000, v154
	v_lshlrev_b32_e32 v162, 16, v155
	v_and_b32_e32 v163, 0xffff0000, v155
	s_waitcnt lgkmcnt(0)
	s_nop 0
	v_mfma_f32_16x16x32_bf16 v[160:163], v[144:147], v[198:201], v[160:163]
	v_mfma_f32_16x16x32_bf16 v[160:163], v[148:151], v[202:205], v[160:163]
	s_cbranch_scc1 .LBB0_907
	s_mov_b32 s5, s1
	s_lshl_b64 s[24:25], s[4:5], 1
	v_lshl_add_u64 v[148:149], v[176:177], 0, s[24:25]
	v_lshl_add_u64 v[156:157], v[178:179], 0, s[24:25]
	global_load_dwordx4 v[144:147], v[148:149], off
	s_nop 0
	global_load_dwordx4 v[148:151], v[148:149], off offset:64
	s_nop 0
	global_load_dwordx4 v[152:155], v[156:157], off offset:16
	s_nop 0
	global_load_dwordx4 v[156:159], v[156:157], off
	s_branch .LBB0_907

.LBB0_1031:
	v_cmp_lt_i32_e32 vcc, v21, v22
	v_mov_b32_e32 v0, v181
	s_ashr_i32 s0, s39, 3
	v_cndmask_b32_e32 v2, v20, v21, vcc
	v_cmp_lt_i32_e32 vcc, v23, v22
	s_waitcnt vmcnt(28)
	v_lshlrev_b32_e32 v33, 2, v2
	v_ashrrev_i32_e32 v2, 6, v0
	v_cndmask_b32_e32 v3, v20, v23, vcc
	v_cmp_lt_i32_e32 vcc, v24, v22
	v_lshlrev_b32_e32 v32, 2, v3
	v_and_b32_e32 v3, 63, v0
	v_cndmask_b32_e32 v4, v20, v24, vcc
	v_cmp_lt_i32_e32 vcc, v25, v22
	v_lshlrev_b32_e32 v31, 2, v4
	v_and_b32_e32 v4, 15, v0
	v_cndmask_b32_e32 v5, v20, v25, vcc
	v_lshlrev_b32_e32 v30, 2, v5
	v_lshrrev_b32_e32 v0, 2, v0
	v_lshlrev_b32_e32 v5, 4, v2
	s_lshl_b32 s1, s39, 7
	v_and_b32_e32 v6, 12, v0
	v_lshlrev_b32_e32 v7, 2, v3
	v_lshlrev_b32_e32 v12, 4, v3
	v_lshl_add_u32 v3, s0, 6, v5
	s_and_b32 s4, s39, 0xfffffc00
	s_and_b32 s8, s1, 0x380
	v_lshlrev_b32_e32 v8, 1, v4
	v_lshlrev_b32_e32 v0, 2, v4
	v_or_b32_e32 v5, v5, v4
	v_or_b32_e32 v4, v3, v6
	s_and_b32 s1, s0, 0x7f
	s_or_b32 s4, s8, s4
	global_load_dword v29, v0, s[40:41]
	global_load_dword v28, v0, s[40:41] offset:64
	global_load_dword v27, v0, s[40:41] offset:128
	global_load_dword v26, v0, s[40:41] offset:192
	v_lshlrev_b32_e32 v0, 1, v6
	v_lshlrev_b32_e32 v6, 6, v5
	v_ashrrev_i32_e32 v5, 31, v4
	s_or_b32 s4, s4, s1
	s_waitcnt vmcnt(28)
	v_lshlrev_b64 v[66:67], 13, v[4:5]
	s_ashr_i32 s5, s4, 31
	v_or_b32_e32 v14, 1, v4
	v_or_b32_e32 v16, 2, v4
	v_or_b32_e32 v18, 3, v4
	v_lshl_add_u64 v[4:5], s[20:21], 0, v[66:67]
	s_lshl_b64 s[0:1], s[4:5], 13
	v_lshl_add_u64 v[4:5], v[4:5], 0, s[8:9]
	s_add_u32 s4, s50, s0
	v_lshl_add_u64 v[50:51], v[4:5], 0, v[8:9]
	s_addc_u32 s5, s51, s1
	v_add_co_u32_e32 v52, vcc, s36, v50
	s_add_u32 s6, s17, s0
	s_nop 0
	v_addc_co_u32_e32 v53, vcc, 0, v51, vcc
	v_lshl_or_b32 v2, v2, 10, v7
	v_ashrrev_i32_e32 v7, 31, v6
	s_addc_u32 s7, s29, s1
	v_add_co_u32_e32 v54, vcc, s37, v50
	v_mov_b32_e32 v1, v9
	v_ashrrev_i32_e32 v3, 31, v2
	v_lshl_add_u64 v[6:7], v[6:7], 1, s[4:5]
	s_add_u32 s0, s15, s0
	v_addc_co_u32_e32 v55, vcc, 0, v51, vcc
	v_mov_b32_e32 v13, v9
	v_lshl_add_u64 v[34:35], v[6:7], 0, v[0:1]
	v_lshl_add_u64 v[36:37], v[2:3], 1, s[6:7]
	s_addc_u32 s1, s16, s1
	v_add_co_u32_e32 v56, vcc, s38, v50
	global_load_dwordx2 v[4:5], v[34:35], off
	global_load_dwordx2 v[6:7], v[34:35], off offset:32
	global_load_dwordx2 v[0:1], v[34:35], off offset:64
	global_load_dwordx2 v[2:3], v[34:35], off offset:96
	global_load_dwordx2 v[68:69], v[36:37], off
	global_load_dwordx2 v[72:73], v[36:37], off offset:512
	global_load_dwordx2 v[76:77], v[36:37], off offset:1024
	global_load_dwordx2 v[80:81], v[36:37], off offset:1536
	v_addc_co_u32_e32 v57, vcc, 0, v51, vcc
	global_load_ushort v82, v[50:51], off offset:3072
	global_load_ushort v83, v[50:51], off offset:3104
	global_load_ushort v84, v[50:51], off offset:3136
	global_load_ushort v85, v[50:51], off offset:3168
	global_load_dwordx4 v[34:37], v12, s[0:1]
	global_load_dwordx4 v[38:41], v12, s[0:1] offset:2048
	global_load_dwordx4 v[42:45], v12, s[0:1] offset:1024
	global_load_dwordx4 v[46:49], v12, s[0:1] offset:3072
	global_load_ushort v86, v[52:53], off offset:3072
	global_load_ushort v87, v[54:55], off offset:3072
	global_load_ushort v88, v[56:57], off offset:3072
	global_load_ushort v89, v[52:53], off offset:3104
	global_load_ushort v90, v[54:55], off offset:3104
	global_load_ushort v91, v[56:57], off offset:3104
	global_load_ushort v92, v[52:53], off offset:3136
	global_load_ushort v93, v[54:55], off offset:3136
	global_load_ushort v94, v[56:57], off offset:3136
	global_load_ushort v95, v[54:55], off offset:3168
	global_load_ushort v96, v[52:53], off offset:3168
	global_load_ushort v97, v[56:57], off offset:3168
	v_lshl_add_u64 v[12:13], s[0:1], 0, v[12:13]
	v_lshl_add_u64 v[70:71], v[12:13], 0, s[10:11]
	s_waitcnt vmcnt(55)
	v_lshl_add_u64 v[74:75], v[12:13], 0, s[12:13]
	v_add_co_u32_e32 v12, vcc, s34, v12
	s_add_u32 s0, s20, s8
	s_nop 0
	v_addc_co_u32_e32 v13, vcc, 0, v13, vcc
	global_load_dwordx4 v[50:53], v[12:13], off
	global_load_dwordx4 v[54:57], v[12:13], off offset:2048
	global_load_dwordx4 v[58:61], v[70:71], off offset:1024
	global_load_dwordx4 v[62:65], v[74:75], off offset:1024
	s_addc_u32 s1, s21, 0
	v_and_b32_e32 v12, 0xffe00000, v66
	v_lshrrev_b32_e32 v13, 5, v66
	v_and_b32_e32 v13, 0xe000, v13
	v_lshrrev_b32_e32 v14, 7, v66
	v_and_b32_e32 v14, 0x7c0, v14
	v_lshrrev_b32_e32 v15, 10, v66
	v_and_b32_e32 v15, 32, v15
	v_and_b32_e32 v16, 30, v8
	v_or3_b32 v12, v12, v13, v14
	v_or3_b32 v12, v12, v15, v16
	s_lshl_b32 s8, s8, 10
	v_add_u32_e32 v12, s8, v12
	v_xor_b32_e32 v16, 16, v12
	v_add_u32_e32 v14, 64, v12
	v_add_u32_e32 v18, 0xc0, v16
	v_add_u32_e32 v16, 0x80, v16
	v_xor_b32_e32 v13, 32, v12
	v_xor_b32_e32 v15, 32, v14
	v_xor_b32_e32 v17, 32, v16
	v_xor_b32_e32 v19, 32, v18
	s_add_i32 s39, s39, s22
	s_cmpk_lt_i32 s39, 0x1000
	s_waitcnt vmcnt(23)
	v_lshlrev_b32_e32 v8, 16, v82
	s_waitcnt vmcnt(22)
	v_lshlrev_b32_e32 v98, 16, v83
	s_waitcnt vmcnt(21)
	v_lshlrev_b32_e32 v99, 16, v84
	s_waitcnt vmcnt(20)
	v_lshlrev_b32_e32 v100, 16, v85
	s_waitcnt vmcnt(19)
	v_mov_b32_e32 v82, v34
	v_mov_b32_e32 v83, v35
	s_waitcnt vmcnt(18)
	v_mov_b32_e32 v84, v38
	v_mov_b32_e32 v85, v39
	s_waitcnt vmcnt(17)
	v_mov_b32_e32 v34, v42
	v_mov_b32_e32 v35, v43
	v_mul_f32_e32 v42, 0xbfb8aa3b, v8
	v_mul_f32_e32 v43, 0xbfb8aa3b, v98
	v_mov_b32_e32 v38, v36
	v_mov_b32_e32 v39, v37
	v_lshlrev_b32_e32 v66, 16, v68
	v_and_b32_e32 v67, 0xffff0000, v68
	v_lshlrev_b32_e32 v68, 16, v69
	v_and_b32_e32 v69, 0xffff0000, v69
	v_lshlrev_b32_e32 v70, 16, v72
	v_and_b32_e32 v71, 0xffff0000, v72
	v_lshlrev_b32_e32 v72, 16, v73
	v_and_b32_e32 v73, 0xffff0000, v73
	s_waitcnt vmcnt(16)
	v_mov_b32_e32 v36, v46
	v_mov_b32_e32 v37, v47
	v_mov_b32_e32 v46, v44
	v_mov_b32_e32 v47, v45
	v_exp_f32_e32 v103, v42
	v_exp_f32_e32 v107, v43
	v_mfma_f32_16x16x32_bf16 v[42:45], v[4:7], v[82:85], v[66:69]
	v_lshlrev_b32_e32 v74, 16, v76
	v_and_b32_e32 v75, 0xffff0000, v76
	v_lshlrev_b32_e32 v76, 16, v77
	v_and_b32_e32 v77, 0xffff0000, v77
	v_lshlrev_b32_e32 v78, 16, v80
	v_and_b32_e32 v79, 0xffff0000, v80
	v_lshlrev_b32_e32 v80, 16, v81
	v_and_b32_e32 v81, 0xffff0000, v81
	s_waitcnt vmcnt(15)
	v_lshlrev_b32_e32 v86, 16, v86
	s_waitcnt vmcnt(14)
	v_lshlrev_b32_e32 v87, 16, v87
	v_mul_f32_e32 v101, 0xbfb8aa3b, v99
	v_mfma_f32_16x16x32_bf16 v[38:41], v[4:7], v[38:41], v[70:73]
	s_waitcnt vmcnt(8)
	v_lshlrev_b32_e32 v93, 16, v93
	s_waitcnt vmcnt(7)
	v_lshlrev_b32_e32 v94, 16, v94
	v_mul_f32_e32 v104, 0xbfb8aa3b, v86
	v_mul_f32_e32 v105, 0xbfb8aa3b, v87
	v_exp_f32_e32 v67, v101
	v_mfma_f32_16x16x32_bf16 v[34:37], v[4:7], v[34:37], v[74:77]
	v_lshlrev_b32_e32 v88, 16, v88
	v_lshlrev_b32_e32 v89, 16, v89
	v_lshlrev_b32_e32 v90, 16, v90
	v_mfma_f32_16x16x32_bf16 v[4:7], v[4:7], v[46:49], v[78:81]
	v_lshlrev_b32_e32 v92, 16, v92
	s_waitcnt vmcnt(5)
	v_lshlrev_b32_e32 v96, 16, v96
	v_lshlrev_b32_e32 v95, 16, v95
	v_mul_f32_e32 v69, 0xbfb8aa3b, v93
	v_mul_f32_e32 v70, 0xbfb8aa3b, v94
	s_waitcnt vmcnt(3)
	v_mov_b32_e32 v46, v50
	v_mov_b32_e32 v47, v51
	s_waitcnt vmcnt(2)
	v_mov_b32_e32 v48, v54
	v_mov_b32_e32 v49, v55
	s_waitcnt vmcnt(1)
	v_mov_b32_e32 v50, v58
	v_mov_b32_e32 v51, v59
	v_exp_f32_e32 v58, v104
	v_exp_f32_e32 v59, v105
	v_lshlrev_b32_e32 v91, 16, v91
	v_mul_f32_e32 v102, 0xbfb8aa3b, v100
	v_lshlrev_b32_e32 v97, 16, v97
	v_mul_f32_e32 v106, 0xbfb8aa3b, v88
	v_mul_f32_e32 v108, 0xbfb8aa3b, v89
	v_mul_f32_e32 v109, 0xbfb8aa3b, v90
	v_mul_f32_e32 v68, 0xbfb8aa3b, v92
	v_mul_f32_e32 v72, 0xbfb8aa3b, v96
	v_mul_f32_e32 v73, 0xbfb8aa3b, v95
	v_mov_b32_e32 v54, v52
	v_mov_b32_e32 v55, v53
	v_mfma_f32_16x16x32_bf16 v[42:45], v[0:3], v[46:49], v[42:45]
	v_exp_f32_e32 v46, v69
	v_exp_f32_e32 v47, v70
	v_mul_f32_e32 v66, 0xbfb8aa3b, v91
	v_exp_f32_e32 v71, v102
	v_mul_f32_e32 v74, 0xbfb8aa3b, v97
	s_waitcnt vmcnt(0)
	v_mov_b32_e32 v52, v62
	v_mov_b32_e32 v53, v63
	v_mov_b32_e32 v62, v60
	v_mov_b32_e32 v63, v61
	v_exp_f32_e32 v60, v106
	v_exp_f32_e32 v61, v108
	v_exp_f32_e32 v75, v109
	v_exp_f32_e32 v68, v68
	v_exp_f32_e32 v48, v72
	v_mfma_f32_16x16x32_bf16 v[38:41], v[0:3], v[54:57], v[38:41]
	v_exp_f32_e32 v49, v73
	v_exp_f32_e32 v66, v66
	v_exp_f32_e32 v54, v74
	v_add_f32_e32 v55, 1.0, v103
	v_mfma_f32_16x16x32_bf16 v[34:37], v[0:3], v[50:53], v[34:37]
	v_add_f32_e32 v50, 1.0, v107
	v_add_f32_e32 v51, 1.0, v67
	v_add_f32_e32 v46, 1.0, v46
	v_mfma_f32_16x16x32_bf16 v[0:3], v[0:3], v[62:65], v[4:7]
	v_rcp_f32_e32 v62, v55
	v_add_f32_e32 v47, 1.0, v47
	v_add_f32_e32 v52, 1.0, v71
	v_add_f32_e32 v4, 1.0, v58
	v_add_f32_e32 v5, 1.0, v59
	v_rcp_f32_e32 v58, v50
	v_rcp_f32_e32 v59, v51
	v_add_f32_e32 v6, 1.0, v60
	v_add_f32_e32 v7, 1.0, v61
	v_add_f32_e32 v50, 1.0, v75
	v_add_f32_e32 v51, 1.0, v68
	v_add_f32_e32 v48, 1.0, v48
	v_add_f32_e32 v49, 1.0, v49
	v_rcp_f32_e32 v61, v4
	v_rcp_f32_e32 v63, v5
	v_rcp_f32_e32 v69, v46
	v_rcp_f32_e32 v70, v47
	v_mov_b32_e32 v4, v42
	v_mov_b32_e32 v5, v38
	v_mov_b32_e32 v46, v43
	v_mov_b32_e32 v47, v39
	v_add_f32_e32 v53, 1.0, v66
	v_rcp_f32_e32 v60, v52
	v_add_f32_e32 v52, 1.0, v54
	v_rcp_f32_e32 v64, v6
	v_rcp_f32_e32 v65, v7
	v_rcp_f32_e32 v66, v50
	v_rcp_f32_e32 v68, v51
	v_rcp_f32_e32 v71, v48
	v_rcp_f32_e32 v72, v49
	v_mov_b32_e32 v6, v34
	v_mov_b32_e32 v7, v0
	v_mov_b32_e32 v48, v35
	v_mov_b32_e32 v49, v1
	v_mov_b32_e32 v50, v44
	v_mov_b32_e32 v51, v40
	v_mov_b32_e32 v54, v45
	v_mov_b32_e32 v55, v41
	v_pk_mul_f32 v[4:5], v[4:5], v[4:5]
	v_pk_mul_f32 v[46:47], v[46:47], v[46:47]
	v_rcp_f32_e32 v67, v53
	v_rcp_f32_e32 v73, v52
	v_mov_b32_e32 v52, v36
	v_mov_b32_e32 v53, v2
	v_mov_b32_e32 v56, v37
	v_mov_b32_e32 v57, v3
	v_mul_f32_e32 v8, v62, v8
	v_mul_f32_e32 v62, v58, v98
	v_mul_f32_e32 v74, v59, v99
	v_pk_mul_f32 v[6:7], v[6:7], v[6:7]
	v_pk_mul_f32 v[48:49], v[48:49], v[48:49]
	v_pk_mul_f32 v[50:51], v[50:51], v[50:51]
	v_pk_mul_f32 v[54:55], v[54:55], v[54:55]
	v_mov_b32_e32 v58, v46
	v_mov_b32_e32 v59, v4
	v_mov_b32_e32 v4, v47
	v_pk_mul_f32 v[52:53], v[52:53], v[52:53]
	v_pk_mul_f32 v[56:57], v[56:57], v[56:57]
	v_mov_b32_e32 v46, v48
	v_mov_b32_e32 v47, v6
	v_mov_b32_e32 v6, v49
	v_mov_b32_e32 v48, v54
	v_mov_b32_e32 v49, v50
	v_mov_b32_e32 v50, v55
	v_pk_add_f32 v[4:5], v[58:59], v[4:5]
	v_mov_b32_e32 v54, v56
	v_mov_b32_e32 v55, v52
	v_pk_add_f32 v[48:49], v[48:49], v[50:51]
	v_pk_add_f32 v[4:5], v[4:5], v[46:47]
	v_mov_b32_e32 v52, v57
	v_pk_add_f32 v[46:47], v[48:49], v[54:55]
	v_pk_add_f32 v[4:5], v[4:5], v[6:7]
	v_pk_add_f32 v[6:7], v[46:47], v[52:53]
	ds_bpermute_b32 v47, v33, v5
	ds_bpermute_b32 v46, v33, v4
	ds_bpermute_b32 v49, v33, v7
	ds_bpermute_b32 v48, v33, v6
	v_mul_f32_e32 v60, v60, v100
	v_mul_f32_e32 v61, v61, v86
	s_waitcnt lgkmcnt(2)
	v_pk_add_f32 v[4:5], v[4:5], v[46:47]
	ds_bpermute_b32 v47, v32, v5
	s_waitcnt lgkmcnt(1)
	v_pk_add_f32 v[6:7], v[6:7], v[48:49]
	ds_bpermute_b32 v46, v32, v4
	ds_bpermute_b32 v33, v32, v7
	ds_bpermute_b32 v32, v32, v6
	v_mul_f32_e32 v63, v63, v87
	v_mul_f32_e32 v64, v64, v88
	s_waitcnt lgkmcnt(2)
	v_pk_add_f32 v[4:5], v[4:5], v[46:47]
	v_mul_f32_e32 v65, v65, v89
	s_waitcnt lgkmcnt(0)
	v_pk_add_f32 v[6:7], v[6:7], v[32:33]
	ds_bpermute_b32 v33, v31, v5
	ds_bpermute_b32 v32, v31, v4
	ds_bpermute_b32 v47, v31, v7
	ds_bpermute_b32 v46, v31, v6
	v_mul_f32_e32 v66, v66, v90
	v_mul_f32_e32 v67, v67, v91
	s_waitcnt lgkmcnt(2)
	v_pk_add_f32 v[4:5], v[4:5], v[32:33]
	ds_bpermute_b32 v33, v30, v5
	s_waitcnt lgkmcnt(1)
	v_pk_add_f32 v[6:7], v[6:7], v[46:47]
	ds_bpermute_b32 v32, v30, v4
	ds_bpermute_b32 v31, v30, v7
	ds_bpermute_b32 v30, v30, v6
	v_mul_f32_e32 v68, v68, v92
	v_mul_f32_e32 v69, v69, v93
	s_waitcnt lgkmcnt(2)
	v_pk_add_f32 v[4:5], v[4:5], v[32:33]
	v_mul_f32_e32 v70, v70, v94
	s_waitcnt lgkmcnt(0)
	v_pk_add_f32 v[6:7], v[6:7], v[30:31]
	v_pk_fma_f32 v[4:5], v[4:5], s[14:15], v[10:11] op_sel_hi:[1,0,0]
	v_pk_fma_f32 v[6:7], v[6:7], s[14:15], v[10:11] op_sel_hi:[1,0,0]
	v_mul_f32_e32 v30, 0x4b800000, v5
	v_cmp_gt_f32_e64 s[6:7], s35, v5
	v_mul_f32_e32 v31, 0x4b800000, v4
	v_cmp_gt_f32_e32 vcc, s35, v4
	v_mul_f32_e32 v32, 0x4b800000, v7
	v_mul_f32_e32 v33, 0x4b800000, v6
	v_cmp_gt_f32_e64 s[0:1], s35, v6
	v_cmp_gt_f32_e64 s[4:5], s35, v7
	v_cndmask_b32_e64 v5, v5, v30, s[6:7]
	v_cndmask_b32_e32 v4, v4, v31, vcc
	v_cndmask_b32_e64 v7, v7, v32, s[4:5]
	v_cndmask_b32_e64 v6, v6, v33, s[0:1]
	v_rsq_f32_e32 v5, v5
	v_rsq_f32_e32 v4, v4
	v_rsq_f32_e32 v7, v7
	v_rsq_f32_e32 v6, v6
	v_mul_f32_e32 v30, 0x45800000, v5
	v_mul_f32_e32 v31, 0x45800000, v4
	v_mul_f32_e32 v32, 0x45800000, v7
	v_mul_f32_e32 v33, 0x45800000, v6
	v_cndmask_b32_e64 v5, v5, v30, s[6:7]
	v_cndmask_b32_e32 v4, v4, v31, vcc
	v_cndmask_b32_e64 v7, v7, v32, s[4:5]
	v_cndmask_b32_e64 v6, v6, v33, s[0:1]
	v_mul_f32_e32 v30, v42, v5
	v_mul_f32_e32 v31, v43, v4
	v_mul_f32_e32 v32, v44, v7
	v_mul_f32_e32 v33, v45, v6
	v_mul_f32_e32 v38, v38, v5
	v_mul_f32_e32 v39, v39, v4
	v_mul_f32_e32 v40, v40, v7
	v_mul_f32_e32 v41, v41, v6
	v_mul_f32_e32 v34, v34, v5
	v_mul_f32_e32 v35, v35, v4
	v_mul_f32_e32 v36, v36, v7
	v_mul_f32_e32 v37, v37, v6
	v_mul_f32_e32 v0, v0, v5
	v_mul_f32_e32 v1, v1, v4
	v_mul_f32_e32 v2, v2, v7
	v_mul_f32_e32 v3, v3, v6
	v_mul_f32_e32 v4, v29, v30
	v_mul_f32_e32 v71, v71, v96
	v_mul_f32_e32 v72, v72, v95
	v_mul_f32_e32 v73, v73, v97
	v_mul_f32_e32 v5, v29, v31
	v_mul_f32_e32 v6, v29, v32
	v_mul_f32_e32 v7, v29, v33
	v_mul_f32_e32 v29, v28, v38
	v_mul_f32_e32 v30, v28, v39
	v_mul_f32_e32 v31, v28, v40
	v_mul_f32_e32 v28, v28, v41
	v_mul_f32_e32 v32, v27, v34
	v_mul_f32_e32 v33, v27, v35
	v_mul_f32_e32 v34, v27, v36
	v_mul_f32_e32 v27, v27, v37
	v_mul_f32_e32 v0, v26, v0
	v_mul_f32_e32 v1, v26, v1
	v_mul_f32_e32 v2, v26, v2
	v_mul_f32_e32 v3, v26, v3
	v_mul_f32_e32 v4, v8, v4
	v_mul_f32_e32 v5, v61, v5
	v_mul_f32_e32 v6, v63, v6
	v_mul_f32_e32 v7, v64, v7
	v_mul_f32_e32 v8, v62, v29
	v_mul_f32_e32 v26, v65, v30
	v_mul_f32_e32 v29, v66, v31
	v_mul_f32_e32 v28, v67, v28
	v_mul_f32_e32 v30, v74, v32
	v_mul_f32_e32 v31, v68, v33
	v_mul_f32_e32 v32, v69, v34
	v_mul_f32_e32 v27, v70, v27
	v_mul_f32_e32 v0, v60, v0
	v_mul_f32_e32 v1, v71, v1
	v_mul_f32_e32 v2, v72, v2
	v_mul_f32_e32 v3, v73, v3
	v_cvt_pk_bf16_f32 v4, v4, s0
	v_cvt_pk_bf16_f32 v5, v5, s0
	v_cvt_pk_bf16_f32 v6, v6, s0
	v_cvt_pk_bf16_f32 v7, v7, s0
	v_cvt_pk_bf16_f32 v8, v8, s0
	v_cvt_pk_bf16_f32 v26, v26, s0
	v_cvt_pk_bf16_f32 v29, v29, s0
	v_cvt_pk_bf16_f32 v28, v28, s0
	v_cvt_pk_bf16_f32 v30, v30, s0
	v_cvt_pk_bf16_f32 v31, v31, s0
	v_cvt_pk_bf16_f32 v32, v32, s0
	v_cvt_pk_bf16_f32 v27, v27, s0
	v_cvt_pk_bf16_f32 v0, v0, s0
	v_cvt_pk_bf16_f32 v1, v1, s0
	v_cvt_pk_bf16_f32 v2, v2, s0
	v_cvt_pk_bf16_f32 v3, v3, s0
	global_store_short v12, v4, s[20:21]
	global_store_short v14, v5, s[20:21]
	global_store_short v16, v6, s[20:21]
	global_store_short v18, v7, s[20:21]
	global_store_short v13, v8, s[20:21]
	global_store_short v15, v26, s[20:21]
	global_store_short v17, v29, s[20:21]
	global_store_short v19, v28, s[20:21]
	global_store_short v12, v30, s[100:101]
	global_store_short v14, v31, s[100:101]
	global_store_short v16, v32, s[100:101]
	global_store_short v18, v27, s[100:101]
	global_store_short v13, v0, s[100:101]
	global_store_short v15, v1, s[100:101]
	global_store_short v17, v2, s[100:101]
	global_store_short v19, v3, s[100:101]
	s_cbranch_scc1 .LBB0_1031
